# gd_task: loader writes beta*v (interior tiles), compute loop variant with one fewer VALU op per step; dual loop for boundary tiles
# speedup vs baseline: 1.0073x; 1.0014x over previous
; __device__ __forceinline__ float fsilu(float x) { return x * fsigmoid(x); }
; __device__ __forceinline__ h16x8 zeroh8() { h16x8 z; for (int i = 0; i < 8; ++i) z[i] = (h16)0.f; return z; }
; __device__ __forceinline__ void conv_silu8(const h16* pc, bool hp, bool hn, const float* cw, float* out) {
;     const h16x8 xc = ldh8(pc), xp = hp ? ldh8(pc - INC) : zeroh8(), xn = hn ? ldh8(pc + INC) : zeroh8();
;     const f32x4 w0a = *(const f32x4*)cw, w0b = *(const f32x4*)(cw + 4), w1a = *(const f32x4*)(cw + 3072), w1b = *(const f32x4*)(cw + 3076), w2a = *(const f32x4*)(cw + 6144), w2b = *(const f32x4*)(cw + 6148);
; #pragma unroll
;     for (int e = 0; e < 8; ++e) { const float a0 = e < 4 ? w0a[e & 3] : w0b[e & 3], a1 = e < 4 ? w1a[e & 3] : w1b[e & 3], a2 = e < 4 ? w2a[e & 3] : w2b[e & 3];
;         out[e] = fsilu((float)xp[e] * a0 + (float)xc[e] * a1 + (float)xn[e] * a2); }
; __device__ __forceinline__ void gd_task(const Params& p, LAS unsigned char* shm, const int tid, const int s, const int d, const int h, const int rq) {
;     ...
;                     const int js = ti * TT + st, t = d ? T - 1 - js : js; const size_t m = (size_t)base + t;
;                     const h16* pr = P + m * INC + GDC; const bool hp = t > 0, hn = t < T - 1;
;                     const h16 bbv = pr[4096 + h], aav = pr[4104 + d * 8 + h];
;                     float q[16], k[16];
;                     conv_silu8(pr + qcol, hp, hn, p.gd_conv + qcol, q); conv_silu8(pr + qcol + 8, hp, hn, p.gd_conv + qcol + 8, q + 8);
;                     conv_silu8(pr + kcol, hp, hn, p.gd_conv + kcol, k); conv_silu8(pr + kcol + 8, hp, hn, p.gd_conv + kcol + 8, k + 8);
;                     float v[4];
;                     { const h16* pc = pr + vcol; const h16x4 xc = *(const h16x4*)pc, xp = hp ? *(const h16x4*)(pc - INC) : (h16x4){(h16)0.f, (h16)0.f, (h16)0.f, (h16)0.f}, xn = hn ? *(const h16x4*)(pc + INC) : (h16x4){(h16)0.f, (h16)0.f, (h16)0.f, (h16)0.f};
;                       const f32x4 a0 = *(const f32x4*)(p.gd_conv + vcol), a1 = *(const f32x4*)(p.gd_conv + 3072 + vcol), a2 = *(const f32x4*)(p.gd_conv + 6144 + vcol);
; #pragma unroll
;                       for (int e = 0; e < 4; ++e) v[e] = fsilu((float)xp[e] * a0[e] + (float)xc[e] * a1[e] + (float)xn[e] * a2[e]); }
.LBB0_333:
	s_cmp_eq_u32 s4, 0x1ff
	s_cbranch_scc1 .Lgdl_slow
	v_add_u32_e32 v2, 64, v204
	v_subrev_u32_e32 v3, 64, v193
	v_cndmask_b32_e64 v7, v3, v2, s[40:41]
	v_add_u32_e32 v4, 0x8000, v7
	v_mov_b64_e32 v[2:3], s[26:27]
	v_mad_i64_i32 v[2:3], s[0:1], v4, s89, v[2:3]
	s_mov_b64 s[0:1], 0x12e05a80
	s_nop 0
	v_lshl_add_u64 v[184:185], v[2:3], 0, s[0:1]
	v_lshl_add_u64 v[2:3], v[184:185], 0, s[16:17]
	v_add_co_u32_e32 v2, vcc, s88, v2
	v_lshl_add_u64 v[4:5], s[48:49], 1, v[184:185]
	s_nop 0
	v_addc_co_u32_e32 v3, vcc, 0, v3, vcc
	v_mov_b32_e32 v149, v0
	v_lshl_add_u64 v[218:219], v[184:185], 0, v[148:149]
	global_load_ushort v199, v[2:3], off
	global_load_ushort v149, v[4:5], off
	s_nop 0
	global_load_dwordx4 v[2:5], v[218:219], off
	v_add_co_u32_e32 v208, vcc, 0xffffc550, v218
	s_nop 1
	v_addc_co_u32_e32 v209, vcc, -1, v219, vcc
	v_add_co_u32_e32 v210, vcc, 0x3ab0, v218
	s_nop 1
	v_addc_co_u32_e32 v211, vcc, 0, v219, vcc
	global_load_dwordx4 v[10:13], v[208:209], off
	global_load_dwordx4 v[6:9], v[210:211], off
	global_load_dwordx4 v[14:17], v[150:151], off offset:16
	global_load_dwordx4 v[26:29], v[150:151], off
	global_load_dwordx4 v[22:25], v[152:153], off offset:16
	global_load_dwordx4 v[34:37], v[152:153], off
	global_load_dwordx4 v[18:21], v[154:155], off offset:16
	global_load_dwordx4 v[30:33], v[154:155], off
	global_load_dwordx4 v[42:45], v[218:219], off offset:16
	global_load_dwordx4 v[46:49], v[208:209], off offset:16
	global_load_dwordx4 v[38:41], v[210:211], off offset:16
	global_load_dwordx4 v[54:57], v[150:151], off offset:48
	global_load_dwordx4 v[66:69], v[150:151], off offset:32
	global_load_dwordx4 v[58:61], v[156:157], off offset:16
	global_load_dwordx4 v[70:73], v[156:157], off
	global_load_dwordx4 v[50:53], v[158:159], off offset:16
	global_load_dwordx4 v[62:65], v[158:159], off
	global_load_dwordx4 v[78:81], v[218:219], off offset:2048
	global_load_dwordx4 v[82:85], v[208:209], off offset:2048
	global_load_dwordx4 v[74:77], v[210:211], off offset:2048
	global_load_dwordx4 v[90:93], v[164:165], off offset:16
	global_load_dwordx4 v[102:105], v[164:165], off
	global_load_dwordx4 v[94:97], v[166:167], off offset:16
	global_load_dwordx4 v[106:109], v[166:167], off
	global_load_dwordx4 v[86:89], v[168:169], off offset:16
	global_load_dwordx4 v[98:101], v[168:169], off
	global_load_dwordx4 v[114:117], v[218:219], off offset:2064
	global_load_dwordx4 v[118:121], v[208:209], off offset:2064
	global_load_dwordx4 v[110:113], v[210:211], off offset:2064
	global_load_dwordx4 v[126:129], v[164:165], off offset:48
	global_load_dwordx4 v[138:141], v[164:165], off offset:32
	global_load_dwordx4 v[130:133], v[170:171], off offset:16
	global_load_dwordx4 v[142:145], v[170:171], off
	global_load_dwordx4 v[122:125], v[172:173], off offset:16
	global_load_dwordx4 v[134:137], v[172:173], off
	v_mov_b32_e32 v175, v0
	v_lshl_add_u64 v[190:191], v[184:185], 0, v[174:175]
	global_load_dwordx2 v[186:187], v[190:191], off
	v_add_co_u32_e32 v214, vcc, 0xffffc550, v190
	s_nop 1
	v_addc_co_u32_e32 v215, vcc, -1, v191, vcc
	v_add_co_u32_e32 v216, vcc, 0x3ab0, v190
	s_nop 1
	v_addc_co_u32_e32 v217, vcc, 0, v191, vcc
	global_load_dwordx2 v[188:189], v[214:215], off
	global_load_dwordx2 v[184:185], v[216:217], off
	global_load_dwordx4 v[220:223], v[176:177], off
	global_load_dwordx4 v[214:217], v[178:179], off
	global_load_dwordx4 v[208:211], v[180:181], off
	s_mov_b32 s6, 0xbfb8aa3b
	s_mov_b32 s0, 1.0
	s_waitcnt vmcnt(33)
	v_fma_mix_f32 v206, v2, v34, 0 op_sel:[0,0,0] op_sel_hi:[1,0,0]
	v_fma_mix_f32 v207, v2, v35, 0 op_sel:[1,0,0] op_sel_hi:[1,0,0]
	v_fma_mix_f32 v218, v3, v36, 0 op_sel:[0,0,0] op_sel_hi:[1,0,0]
	v_fma_mix_f32 v219, v3, v37, 0 op_sel:[1,0,0] op_sel_hi:[1,0,0]
	v_fma_mix_f32 v206, v10, v26, v206 op_sel:[0,0,0] op_sel_hi:[1,0,0]
	v_fma_mix_f32 v207, v10, v27, v207 op_sel:[1,0,0] op_sel_hi:[1,0,0]
	v_fma_mix_f32 v218, v11, v28, v218 op_sel:[0,0,0] op_sel_hi:[1,0,0]
	v_fma_mix_f32 v219, v11, v29, v219 op_sel:[1,0,0] op_sel_hi:[1,0,0]
	v_fma_mix_f32 v206, v6, v30, v206 op_sel:[0,0,0] op_sel_hi:[1,0,0]
	v_fma_mix_f32 v207, v6, v31, v207 op_sel:[1,0,0] op_sel_hi:[1,0,0]
	v_fma_mix_f32 v218, v7, v32, v218 op_sel:[0,0,0] op_sel_hi:[1,0,0]
	v_fma_mix_f32 v219, v7, v33, v219 op_sel:[1,0,0] op_sel_hi:[1,0,0]
	v_pk_mul_f32 v[240:241], v[206:207], s[6:7] op_sel_hi:[1,0]
	v_pk_mul_f32 v[190:191], v[218:219], s[6:7] op_sel_hi:[1,0]
	v_exp_f32_e32 v240, v240
	v_exp_f32_e32 v241, v241
	v_exp_f32_e32 v190, v190
	v_exp_f32_e32 v191, v191
	v_pk_add_f32 v[240:241], v[240:241], s[0:1] op_sel_hi:[1,0]
	v_pk_add_f32 v[190:191], v[190:191], s[0:1] op_sel_hi:[1,0]
	v_rcp_f32_e32 v240, v240
	v_rcp_f32_e32 v241, v241
	v_rcp_f32_e32 v190, v190
	v_rcp_f32_e32 v191, v191
	v_pk_mul_f32 v[34:35], v[206:207], v[240:241]
	v_pk_mul_f32 v[36:37], v[218:219], v[190:191]
	v_fma_mix_f32 v206, v4, v22, 0 op_sel:[0,0,0] op_sel_hi:[1,0,0]
	v_fma_mix_f32 v207, v4, v23, 0 op_sel:[1,0,0] op_sel_hi:[1,0,0]
	v_fma_mix_f32 v218, v5, v24, 0 op_sel:[0,0,0] op_sel_hi:[1,0,0]
	v_fma_mix_f32 v219, v5, v25, 0 op_sel:[1,0,0] op_sel_hi:[1,0,0]
	v_fma_mix_f32 v206, v12, v14, v206 op_sel:[0,0,0] op_sel_hi:[1,0,0]
	v_fma_mix_f32 v207, v12, v15, v207 op_sel:[1,0,0] op_sel_hi:[1,0,0]
	v_fma_mix_f32 v218, v13, v16, v218 op_sel:[0,0,0] op_sel_hi:[1,0,0]
	v_fma_mix_f32 v219, v13, v17, v219 op_sel:[1,0,0] op_sel_hi:[1,0,0]
	v_fma_mix_f32 v206, v8, v18, v206 op_sel:[0,0,0] op_sel_hi:[1,0,0]
	v_fma_mix_f32 v207, v8, v19, v207 op_sel:[1,0,0] op_sel_hi:[1,0,0]
	v_fma_mix_f32 v218, v9, v20, v218 op_sel:[0,0,0] op_sel_hi:[1,0,0]
	v_fma_mix_f32 v219, v9, v21, v219 op_sel:[1,0,0] op_sel_hi:[1,0,0]
	v_pk_mul_f32 v[240:241], v[206:207], s[6:7] op_sel_hi:[1,0]
	v_pk_mul_f32 v[190:191], v[218:219], s[6:7] op_sel_hi:[1,0]
	v_exp_f32_e32 v240, v240
	v_exp_f32_e32 v241, v241
	v_exp_f32_e32 v190, v190
	v_exp_f32_e32 v191, v191
	v_pk_add_f32 v[240:241], v[240:241], s[0:1] op_sel_hi:[1,0]
	v_pk_add_f32 v[190:191], v[190:191], s[0:1] op_sel_hi:[1,0]
	v_rcp_f32_e32 v240, v240
	v_rcp_f32_e32 v241, v241
	v_rcp_f32_e32 v190, v190
	v_rcp_f32_e32 v191, v191
	v_pk_mul_f32 v[22:23], v[206:207], v[240:241]
	v_pk_mul_f32 v[24:25], v[218:219], v[190:191]
	s_waitcnt vmcnt(24)
; __device__ __forceinline__ float fsilu(float x) { return x * fsigmoid(x); }
; __device__ __forceinline__ h16x8 zeroh8() { h16x8 z; for (int i = 0; i < 8; ++i) z[i] = (h16)0.f; return z; }
; __device__ __forceinline__ void conv_silu8(const h16* pc, bool hp, bool hn, const float* cw, float* out) {
;     const h16x8 xc = ldh8(pc), xp = hp ? ldh8(pc - INC) : zeroh8(), xn = hn ? ldh8(pc + INC) : zeroh8();
;     const f32x4 w0a = *(const f32x4*)cw, w0b = *(const f32x4*)(cw + 4), w1a = *(const f32x4*)(cw + 3072), w1b = *(const f32x4*)(cw + 3076), w2a = *(const f32x4*)(cw + 6144), w2b = *(const f32x4*)(cw + 6148);
; #pragma unroll
;     for (int e = 0; e < 8; ++e) { const float a0 = e < 4 ? w0a[e & 3] : w0b[e & 3], a1 = e < 4 ? w1a[e & 3] : w1b[e & 3], a2 = e < 4 ? w2a[e & 3] : w2b[e & 3];
;         out[e] = fsilu((float)xp[e] * a0 + (float)xc[e] * a1 + (float)xn[e] * a2); }
	v_fma_mix_f32 v206, v42, v70, 0 op_sel:[0,0,0] op_sel_hi:[1,0,0]
	v_fma_mix_f32 v207, v42, v71, 0 op_sel:[1,0,0] op_sel_hi:[1,0,0]
	v_fma_mix_f32 v218, v43, v72, 0 op_sel:[0,0,0] op_sel_hi:[1,0,0]
	v_fma_mix_f32 v219, v43, v73, 0 op_sel:[1,0,0] op_sel_hi:[1,0,0]
	v_fma_mix_f32 v206, v46, v66, v206 op_sel:[0,0,0] op_sel_hi:[1,0,0]
	v_fma_mix_f32 v207, v46, v67, v207 op_sel:[1,0,0] op_sel_hi:[1,0,0]
	v_fma_mix_f32 v218, v47, v68, v218 op_sel:[0,0,0] op_sel_hi:[1,0,0]
	v_fma_mix_f32 v219, v47, v69, v219 op_sel:[1,0,0] op_sel_hi:[1,0,0]
	v_fma_mix_f32 v206, v38, v62, v206 op_sel:[0,0,0] op_sel_hi:[1,0,0]
	v_fma_mix_f32 v207, v38, v63, v207 op_sel:[1,0,0] op_sel_hi:[1,0,0]
	v_fma_mix_f32 v218, v39, v64, v218 op_sel:[0,0,0] op_sel_hi:[1,0,0]
	v_fma_mix_f32 v219, v39, v65, v219 op_sel:[1,0,0] op_sel_hi:[1,0,0]
	v_pk_mul_f32 v[240:241], v[206:207], s[6:7] op_sel_hi:[1,0]
	v_pk_mul_f32 v[190:191], v[218:219], s[6:7] op_sel_hi:[1,0]
	v_exp_f32_e32 v240, v240
	v_exp_f32_e32 v241, v241
	v_exp_f32_e32 v190, v190
	v_exp_f32_e32 v191, v191
	v_pk_add_f32 v[240:241], v[240:241], s[0:1] op_sel_hi:[1,0]
	v_pk_add_f32 v[190:191], v[190:191], s[0:1] op_sel_hi:[1,0]
	v_rcp_f32_e32 v240, v240
	v_rcp_f32_e32 v241, v241
	v_rcp_f32_e32 v190, v190
	v_rcp_f32_e32 v191, v191
	v_pk_mul_f32 v[70:71], v[206:207], v[240:241]
	v_pk_mul_f32 v[72:73], v[218:219], v[190:191]
	v_fma_mix_f32 v206, v44, v58, 0 op_sel:[0,0,0] op_sel_hi:[1,0,0]
	v_fma_mix_f32 v207, v44, v59, 0 op_sel:[1,0,0] op_sel_hi:[1,0,0]
	v_fma_mix_f32 v218, v45, v60, 0 op_sel:[0,0,0] op_sel_hi:[1,0,0]
	v_fma_mix_f32 v219, v45, v61, 0 op_sel:[1,0,0] op_sel_hi:[1,0,0]
	v_fma_mix_f32 v206, v48, v54, v206 op_sel:[0,0,0] op_sel_hi:[1,0,0]
	v_fma_mix_f32 v207, v48, v55, v207 op_sel:[1,0,0] op_sel_hi:[1,0,0]
	v_fma_mix_f32 v218, v49, v56, v218 op_sel:[0,0,0] op_sel_hi:[1,0,0]
	v_fma_mix_f32 v219, v49, v57, v219 op_sel:[1,0,0] op_sel_hi:[1,0,0]
	v_fma_mix_f32 v206, v40, v50, v206 op_sel:[0,0,0] op_sel_hi:[1,0,0]
	v_fma_mix_f32 v207, v40, v51, v207 op_sel:[1,0,0] op_sel_hi:[1,0,0]
	v_fma_mix_f32 v218, v41, v52, v218 op_sel:[0,0,0] op_sel_hi:[1,0,0]
	v_fma_mix_f32 v219, v41, v53, v219 op_sel:[1,0,0] op_sel_hi:[1,0,0]
	v_pk_mul_f32 v[240:241], v[206:207], s[6:7] op_sel_hi:[1,0]
	v_pk_mul_f32 v[190:191], v[218:219], s[6:7] op_sel_hi:[1,0]
	v_exp_f32_e32 v240, v240
	v_exp_f32_e32 v241, v241
	v_exp_f32_e32 v190, v190
	v_exp_f32_e32 v191, v191
	v_pk_add_f32 v[240:241], v[240:241], s[0:1] op_sel_hi:[1,0]
	v_pk_add_f32 v[190:191], v[190:191], s[0:1] op_sel_hi:[1,0]
	v_rcp_f32_e32 v240, v240
	v_rcp_f32_e32 v241, v241
	v_rcp_f32_e32 v190, v190
	v_rcp_f32_e32 v191, v191
	v_pk_mul_f32 v[58:59], v[206:207], v[240:241]
	v_pk_mul_f32 v[60:61], v[218:219], v[190:191]
	s_waitcnt vmcnt(15)
	v_fma_mix_f32 v206, v78, v106, 0 op_sel:[0,0,0] op_sel_hi:[1,0,0]
	v_fma_mix_f32 v207, v78, v107, 0 op_sel:[1,0,0] op_sel_hi:[1,0,0]
	v_fma_mix_f32 v218, v79, v108, 0 op_sel:[0,0,0] op_sel_hi:[1,0,0]
	v_fma_mix_f32 v219, v79, v109, 0 op_sel:[1,0,0] op_sel_hi:[1,0,0]
	v_fma_mix_f32 v206, v82, v102, v206 op_sel:[0,0,0] op_sel_hi:[1,0,0]
	v_fma_mix_f32 v207, v82, v103, v207 op_sel:[1,0,0] op_sel_hi:[1,0,0]
	v_fma_mix_f32 v218, v83, v104, v218 op_sel:[0,0,0] op_sel_hi:[1,0,0]
	v_fma_mix_f32 v219, v83, v105, v219 op_sel:[1,0,0] op_sel_hi:[1,0,0]
	v_fma_mix_f32 v206, v74, v98, v206 op_sel:[0,0,0] op_sel_hi:[1,0,0]
	v_fma_mix_f32 v207, v74, v99, v207 op_sel:[1,0,0] op_sel_hi:[1,0,0]
	v_fma_mix_f32 v218, v75, v100, v218 op_sel:[0,0,0] op_sel_hi:[1,0,0]
	v_fma_mix_f32 v219, v75, v101, v219 op_sel:[1,0,0] op_sel_hi:[1,0,0]
	v_pk_mul_f32 v[240:241], v[206:207], s[6:7] op_sel_hi:[1,0]
	v_pk_mul_f32 v[190:191], v[218:219], s[6:7] op_sel_hi:[1,0]
	v_exp_f32_e32 v240, v240
	v_exp_f32_e32 v241, v241
	v_exp_f32_e32 v190, v190
	v_exp_f32_e32 v191, v191
	v_pk_add_f32 v[240:241], v[240:241], s[0:1] op_sel_hi:[1,0]
	v_pk_add_f32 v[190:191], v[190:191], s[0:1] op_sel_hi:[1,0]
	v_rcp_f32_e32 v240, v240
	v_rcp_f32_e32 v241, v241
	v_rcp_f32_e32 v190, v190
	v_rcp_f32_e32 v191, v191
	v_pk_mul_f32 v[106:107], v[206:207], v[240:241]
	v_pk_mul_f32 v[108:109], v[218:219], v[190:191]
	v_fma_mix_f32 v206, v80, v94, 0 op_sel:[0,0,0] op_sel_hi:[1,0,0]
	v_fma_mix_f32 v207, v80, v95, 0 op_sel:[1,0,0] op_sel_hi:[1,0,0]
	v_fma_mix_f32 v218, v81, v96, 0 op_sel:[0,0,0] op_sel_hi:[1,0,0]
	v_fma_mix_f32 v219, v81, v97, 0 op_sel:[1,0,0] op_sel_hi:[1,0,0]
	v_fma_mix_f32 v206, v84, v90, v206 op_sel:[0,0,0] op_sel_hi:[1,0,0]
	v_fma_mix_f32 v207, v84, v91, v207 op_sel:[1,0,0] op_sel_hi:[1,0,0]
	v_fma_mix_f32 v218, v85, v92, v218 op_sel:[0,0,0] op_sel_hi:[1,0,0]
	v_fma_mix_f32 v219, v85, v93, v219 op_sel:[1,0,0] op_sel_hi:[1,0,0]
	v_fma_mix_f32 v206, v76, v86, v206 op_sel:[0,0,0] op_sel_hi:[1,0,0]
	v_fma_mix_f32 v207, v76, v87, v207 op_sel:[1,0,0] op_sel_hi:[1,0,0]
	v_fma_mix_f32 v218, v77, v88, v218 op_sel:[0,0,0] op_sel_hi:[1,0,0]
	v_fma_mix_f32 v219, v77, v89, v219 op_sel:[1,0,0] op_sel_hi:[1,0,0]
	v_pk_mul_f32 v[240:241], v[206:207], s[6:7] op_sel_hi:[1,0]
	v_pk_mul_f32 v[190:191], v[218:219], s[6:7] op_sel_hi:[1,0]
	v_exp_f32_e32 v240, v240
	v_exp_f32_e32 v241, v241
	v_exp_f32_e32 v190, v190
	v_exp_f32_e32 v191, v191
	v_pk_add_f32 v[240:241], v[240:241], s[0:1] op_sel_hi:[1,0]
	v_pk_add_f32 v[190:191], v[190:191], s[0:1] op_sel_hi:[1,0]
	v_rcp_f32_e32 v240, v240
	v_rcp_f32_e32 v241, v241
	v_rcp_f32_e32 v190, v190
	v_rcp_f32_e32 v191, v191
	v_pk_mul_f32 v[94:95], v[206:207], v[240:241]
	v_pk_mul_f32 v[96:97], v[218:219], v[190:191]
	s_waitcnt vmcnt(6)
; __device__ __forceinline__ float fsilu(float x) { return x * fsigmoid(x); }
; __device__ __forceinline__ h16x8 zeroh8() { h16x8 z; for (int i = 0; i < 8; ++i) z[i] = (h16)0.f; return z; }
; __device__ __forceinline__ void conv_silu8(const h16* pc, bool hp, bool hn, const float* cw, float* out) {
;     const h16x8 xc = ldh8(pc), xp = hp ? ldh8(pc - INC) : zeroh8(), xn = hn ? ldh8(pc + INC) : zeroh8();
;     const f32x4 w0a = *(const f32x4*)cw, w0b = *(const f32x4*)(cw + 4), w1a = *(const f32x4*)(cw + 3072), w1b = *(const f32x4*)(cw + 3076), w2a = *(const f32x4*)(cw + 6144), w2b = *(const f32x4*)(cw + 6148);
; #pragma unroll
;     for (int e = 0; e < 8; ++e) { const float a0 = e < 4 ? w0a[e & 3] : w0b[e & 3], a1 = e < 4 ? w1a[e & 3] : w1b[e & 3], a2 = e < 4 ? w2a[e & 3] : w2b[e & 3];
;         out[e] = fsilu((float)xp[e] * a0 + (float)xc[e] * a1 + (float)xn[e] * a2); }
	v_fma_mix_f32 v206, v114, v142, 0 op_sel:[0,0,0] op_sel_hi:[1,0,0]
	v_fma_mix_f32 v207, v114, v143, 0 op_sel:[1,0,0] op_sel_hi:[1,0,0]
	v_fma_mix_f32 v218, v115, v144, 0 op_sel:[0,0,0] op_sel_hi:[1,0,0]
	v_fma_mix_f32 v219, v115, v145, 0 op_sel:[1,0,0] op_sel_hi:[1,0,0]
	v_fma_mix_f32 v206, v118, v138, v206 op_sel:[0,0,0] op_sel_hi:[1,0,0]
	v_fma_mix_f32 v207, v118, v139, v207 op_sel:[1,0,0] op_sel_hi:[1,0,0]
	v_fma_mix_f32 v218, v119, v140, v218 op_sel:[0,0,0] op_sel_hi:[1,0,0]
	v_fma_mix_f32 v219, v119, v141, v219 op_sel:[1,0,0] op_sel_hi:[1,0,0]
	v_fma_mix_f32 v206, v110, v134, v206 op_sel:[0,0,0] op_sel_hi:[1,0,0]
	v_fma_mix_f32 v207, v110, v135, v207 op_sel:[1,0,0] op_sel_hi:[1,0,0]
	v_fma_mix_f32 v218, v111, v136, v218 op_sel:[0,0,0] op_sel_hi:[1,0,0]
	v_fma_mix_f32 v219, v111, v137, v219 op_sel:[1,0,0] op_sel_hi:[1,0,0]
	v_pk_mul_f32 v[240:241], v[206:207], s[6:7] op_sel_hi:[1,0]
	v_pk_mul_f32 v[190:191], v[218:219], s[6:7] op_sel_hi:[1,0]
	v_exp_f32_e32 v240, v240
	v_exp_f32_e32 v241, v241
	v_exp_f32_e32 v190, v190
	v_exp_f32_e32 v191, v191
	v_pk_add_f32 v[240:241], v[240:241], s[0:1] op_sel_hi:[1,0]
	v_pk_add_f32 v[190:191], v[190:191], s[0:1] op_sel_hi:[1,0]
	v_rcp_f32_e32 v240, v240
	v_rcp_f32_e32 v241, v241
	v_rcp_f32_e32 v190, v190
	v_rcp_f32_e32 v191, v191
	v_pk_mul_f32 v[142:143], v[206:207], v[240:241]
	v_pk_mul_f32 v[144:145], v[218:219], v[190:191]
	v_fma_mix_f32 v206, v116, v130, 0 op_sel:[0,0,0] op_sel_hi:[1,0,0]
	v_fma_mix_f32 v207, v116, v131, 0 op_sel:[1,0,0] op_sel_hi:[1,0,0]
	v_fma_mix_f32 v218, v117, v132, 0 op_sel:[0,0,0] op_sel_hi:[1,0,0]
	v_fma_mix_f32 v219, v117, v133, 0 op_sel:[1,0,0] op_sel_hi:[1,0,0]
	v_fma_mix_f32 v206, v120, v126, v206 op_sel:[0,0,0] op_sel_hi:[1,0,0]
	v_fma_mix_f32 v207, v120, v127, v207 op_sel:[1,0,0] op_sel_hi:[1,0,0]
	v_fma_mix_f32 v218, v121, v128, v218 op_sel:[0,0,0] op_sel_hi:[1,0,0]
	v_fma_mix_f32 v219, v121, v129, v219 op_sel:[1,0,0] op_sel_hi:[1,0,0]
	v_fma_mix_f32 v206, v112, v122, v206 op_sel:[0,0,0] op_sel_hi:[1,0,0]
	v_fma_mix_f32 v207, v112, v123, v207 op_sel:[1,0,0] op_sel_hi:[1,0,0]
	v_fma_mix_f32 v218, v113, v124, v218 op_sel:[0,0,0] op_sel_hi:[1,0,0]
	v_fma_mix_f32 v219, v113, v125, v219 op_sel:[1,0,0] op_sel_hi:[1,0,0]
	v_pk_mul_f32 v[240:241], v[206:207], s[6:7] op_sel_hi:[1,0]
	v_pk_mul_f32 v[190:191], v[218:219], s[6:7] op_sel_hi:[1,0]
	v_exp_f32_e32 v240, v240
	v_exp_f32_e32 v241, v241
	v_exp_f32_e32 v190, v190
	v_exp_f32_e32 v191, v191
	v_pk_add_f32 v[240:241], v[240:241], s[0:1] op_sel_hi:[1,0]
	v_pk_add_f32 v[190:191], v[190:191], s[0:1] op_sel_hi:[1,0]
	v_rcp_f32_e32 v240, v240
	v_rcp_f32_e32 v241, v241
	v_rcp_f32_e32 v190, v190
	v_rcp_f32_e32 v191, v191
	v_pk_mul_f32 v[130:131], v[206:207], v[240:241]
	v_pk_mul_f32 v[132:133], v[218:219], v[190:191]
	s_waitcnt vmcnt(0)
; #define LAS __attribute__((address_space(3)))
; __device__ __forceinline__ float fsigmoid(float x) { return __builtin_amdgcn_rcpf(1.0f + __expf(-x)); }
; __device__ __forceinline__ float fsilu(float x) { return x * fsigmoid(x); }
; __device__ __forceinline__ void gd_task(const Params& p, LAS unsigned char* shm, const int tid, const int s, const int d, const int h, const int rq) {
;     ...
;                     { const h16* pc = pr + vcol; const h16x4 xc = *(const h16x4*)pc, xp = hp ? *(const h16x4*)(pc - INC) : (h16x4){(h16)0.f, (h16)0.f, (h16)0.f, (h16)0.f}, xn = hn ? *(const h16x4*)(pc + INC) : (h16x4){(h16)0.f, (h16)0.f, (h16)0.f, (h16)0.f};
;                       const f32x4 a0 = *(const f32x4*)(p.gd_conv + vcol), a1 = *(const f32x4*)(p.gd_conv + 3072 + vcol), a2 = *(const f32x4*)(p.gd_conv + 6144 + vcol);
; #pragma unroll
;                       for (int e = 0; e < 4; ++e) v[e] = fsilu((float)xp[e] * a0[e] + (float)xc[e] * a1[e] + (float)xn[e] * a2[e]); }
;                     float nq = 0.f, nk = 0.f;
; #pragma unroll
;                     for (int e = 0; e < 16; ++e) { nq += q[e] * q[e]; nk += k[e] * k[e]; }
;                     nq = red8(nq); nk = red8(nk);
;                     const float rq_ = rsqrtf(nq + 1e-6f) * 0.08838834764831845f, rk_ = rsqrtf(nk + 1e-6f);
;                     float kq = 0.f;
; #pragma unroll
;                     for (int e = 0; e < 16; ++e) { q[e] *= rq_; k[e] *= rk_; kq += q[e] * k[e]; }
;                     kq = red8(kq);
;                     LAS float* sb = inb + (ti & 1) * GD_INF + st * GD_STRIDE;
; #pragma unroll
;                     for (int e = 0; e < 4; ++e) { *(LAS f32x4*)(sb + 20 * jj + 4 * e) = (f32x4){k[4 * e], k[4 * e + 1], k[4 * e + 2], k[4 * e + 3]};
;                         *(LAS f32x4*)(sb + 160 + 20 * jj + 4 * e) = (f32x4){q[4 * e], q[4 * e + 1], q[4 * e + 2], q[4 * e + 3]}; }
;                     *(LAS f32x4*)(sb + 320 + 4 * jj) = (f32x4){v[0], v[1], v[2], v[3]};
;                     if (jj == 0) { const float beta = fsigmoid((float)bbv); const float ain = (float)aav;
	v_fma_mix_f32 v206, v186, v214, 0 op_sel:[0,0,0] op_sel_hi:[1,0,0]
	v_fma_mix_f32 v207, v186, v215, 0 op_sel:[1,0,0] op_sel_hi:[1,0,0]
	v_fma_mix_f32 v218, v187, v216, 0 op_sel:[0,0,0] op_sel_hi:[1,0,0]
	v_fma_mix_f32 v219, v187, v217, 0 op_sel:[1,0,0] op_sel_hi:[1,0,0]
	v_fma_mix_f32 v206, v188, v220, v206 op_sel:[0,0,0] op_sel_hi:[1,0,0]
	v_fma_mix_f32 v207, v188, v221, v207 op_sel:[1,0,0] op_sel_hi:[1,0,0]
	v_fma_mix_f32 v218, v189, v222, v218 op_sel:[0,0,0] op_sel_hi:[1,0,0]
	v_fma_mix_f32 v219, v189, v223, v219 op_sel:[1,0,0] op_sel_hi:[1,0,0]
	v_fma_mix_f32 v206, v184, v208, v206 op_sel:[0,0,0] op_sel_hi:[1,0,0]
	v_fma_mix_f32 v207, v184, v209, v207 op_sel:[1,0,0] op_sel_hi:[1,0,0]
	v_fma_mix_f32 v218, v185, v210, v218 op_sel:[0,0,0] op_sel_hi:[1,0,0]
	v_fma_mix_f32 v219, v185, v211, v219 op_sel:[1,0,0] op_sel_hi:[1,0,0]
	v_pk_mul_f32 v[240:241], v[206:207], s[6:7] op_sel_hi:[1,0]
	v_pk_mul_f32 v[190:191], v[218:219], s[6:7] op_sel_hi:[1,0]
	v_exp_f32_e32 v240, v240
	v_exp_f32_e32 v241, v241
	v_exp_f32_e32 v190, v190
	v_exp_f32_e32 v191, v191
	v_pk_add_f32 v[240:241], v[240:241], s[0:1] op_sel_hi:[1,0]
	v_pk_add_f32 v[190:191], v[190:191], s[0:1] op_sel_hi:[1,0]
	v_rcp_f32_e32 v240, v240
	v_rcp_f32_e32 v241, v241
	v_rcp_f32_e32 v190, v190
	v_rcp_f32_e32 v191, v191
	v_pk_mul_f32 v[214:215], v[206:207], v[240:241]
	v_pk_mul_f32 v[216:217], v[218:219], v[190:191]
	v_cvt_f32_f16_e32 v240, v199
	s_nop 0
	v_mul_f32_e32 v240, 0xbfb8aa3b, v240
	v_exp_f32_e32 v240, v240
	s_nop 0
	v_add_f32_e32 v240, 1.0, v240
	v_rcp_f32_e32 v240, v240
	s_nop 0
	v_pk_mul_f32 v[214:215], v[214:215], v[240:241] op_sel_hi:[1,0]
	v_pk_mul_f32 v[216:217], v[216:217], v[240:241] op_sel_hi:[1,0]
	v_pk_mul_f32 v[206:207], v[34:35], v[34:35]
	v_pk_mul_f32 v[218:219], v[106:107], v[106:107]
	v_pk_fma_f32 v[206:207], v[36:37], v[36:37], v[206:207]
	v_pk_fma_f32 v[218:219], v[108:109], v[108:109], v[218:219]
	v_pk_fma_f32 v[206:207], v[22:23], v[22:23], v[206:207]
	v_pk_fma_f32 v[218:219], v[94:95], v[94:95], v[218:219]
	v_pk_fma_f32 v[206:207], v[24:25], v[24:25], v[206:207]
	v_pk_fma_f32 v[218:219], v[96:97], v[96:97], v[218:219]
	v_pk_fma_f32 v[206:207], v[70:71], v[70:71], v[206:207]
	v_pk_fma_f32 v[218:219], v[142:143], v[142:143], v[218:219]
	v_pk_fma_f32 v[206:207], v[72:73], v[72:73], v[206:207]
	v_pk_fma_f32 v[218:219], v[144:145], v[144:145], v[218:219]
	v_pk_fma_f32 v[206:207], v[58:59], v[58:59], v[206:207]
	v_pk_fma_f32 v[218:219], v[130:131], v[130:131], v[218:219]
	v_pk_fma_f32 v[206:207], v[60:61], v[60:61], v[206:207]
	v_pk_fma_f32 v[218:219], v[132:133], v[132:133], v[218:219]
	s_bitcmp1_b32 s4, 0
	v_add_f32_e32 v240, v206, v207
	v_add_f32_e32 v241, v218, v219
	s_cselect_b32 s0, 0xb200, 0
	v_add_f32_dpp v240, v240, v240 quad_perm:[1,0,3,2] row_mask:0xf bank_mask:0xf bound_ctrl:1
	v_add_f32_dpp v241, v241, v241 quad_perm:[1,0,3,2] row_mask:0xf bank_mask:0xf bound_ctrl:1
	v_add_u32_e32 v8, s0, v196
	v_add_f32_dpp v240, v240, v240 quad_perm:[2,3,0,1] row_mask:0xf bank_mask:0xf bound_ctrl:1
	v_add_f32_dpp v241, v241, v241 quad_perm:[2,3,0,1] row_mask:0xf bank_mask:0xf bound_ctrl:1
	v_lshl_add_u32 v212, v200, 2, v8
	v_add_f32_dpp v240, v240, v240 row_half_mirror row_mask:0xf bank_mask:0xf bound_ctrl:1
	v_add_f32_dpp v241, v241, v241 row_half_mirror row_mask:0xf bank_mask:0xf bound_ctrl:1
	v_add_u32_e32 v205, v212, v201
	s_nop 0
	v_add_f32_e32 v240, 0x358637bd, v240
	v_add_f32_e32 v241, 0x358637bd, v241
	v_rsq_f32_e32 v240, v240
	v_rsq_f32_e32 v241, v241
	s_nop 0
	v_mul_f32_e32 v240, 0x3db504f3, v240
	s_nop 0
	v_pk_mul_f32 v[2:3], v[34:35], v[240:241] op_sel_hi:[1,0]
	v_pk_mul_f32 v[18:19], v[106:107], v[240:241] op_sel:[0,1] op_sel_hi:[1,1]
	v_pk_mul_f32 v[4:5], v[36:37], v[240:241] op_sel_hi:[1,0]
	v_pk_mul_f32 v[20:21], v[108:109], v[240:241] op_sel:[0,1] op_sel_hi:[1,1]
	v_pk_mul_f32 v[42:43], v[22:23], v[240:241] op_sel_hi:[1,0]
	v_pk_mul_f32 v[26:27], v[94:95], v[240:241] op_sel:[0,1] op_sel_hi:[1,1]
	v_pk_mul_f32 v[44:45], v[24:25], v[240:241] op_sel_hi:[1,0]
	v_pk_mul_f32 v[28:29], v[96:97], v[240:241] op_sel:[0,1] op_sel_hi:[1,1]
	v_pk_mul_f32 v[46:47], v[70:71], v[240:241] op_sel_hi:[1,0]
	v_pk_mul_f32 v[30:31], v[142:143], v[240:241] op_sel:[0,1] op_sel_hi:[1,1]
	v_pk_mul_f32 v[48:49], v[72:73], v[240:241] op_sel_hi:[1,0]
	v_pk_mul_f32 v[32:33], v[144:145], v[240:241] op_sel:[0,1] op_sel_hi:[1,1]
	v_pk_mul_f32 v[14:15], v[58:59], v[240:241] op_sel_hi:[1,0]
	v_pk_mul_f32 v[38:39], v[130:131], v[240:241] op_sel:[0,1] op_sel_hi:[1,1]
	v_pk_mul_f32 v[16:17], v[60:61], v[240:241] op_sel_hi:[1,0]
	v_pk_mul_f32 v[40:41], v[132:133], v[240:241] op_sel:[0,1] op_sel_hi:[1,1]
	v_pk_mul_f32 v[190:191], v[2:3], v[18:19]
	v_pk_fma_f32 v[190:191], v[4:5], v[20:21], v[190:191]
	v_pk_fma_f32 v[190:191], v[42:43], v[26:27], v[190:191]
	v_pk_fma_f32 v[190:191], v[44:45], v[28:29], v[190:191]
	v_pk_fma_f32 v[190:191], v[46:47], v[30:31], v[190:191]
	v_pk_fma_f32 v[190:191], v[48:49], v[32:33], v[190:191]
	v_pk_fma_f32 v[190:191], v[14:15], v[38:39], v[190:191]
	v_pk_fma_f32 v[190:191], v[16:17], v[40:41], v[190:191]
	ds_write_b128 v212, v[18:21]
	v_add_f32_e32 v9, v190, v191
	ds_write_b128 v212, v[2:5] offset:640
	ds_write_b128 v212, v[26:29] offset:16
	v_add_f32_dpp v9, v9, v9 quad_perm:[1,0,3,2] row_mask:0xf bank_mask:0xf bound_ctrl:1
	ds_write_b128 v212, v[42:45] offset:656
	ds_write_b128 v212, v[30:33] offset:32
	v_add_f32_dpp v9, v9, v9 quad_perm:[2,3,0,1] row_mask:0xf bank_mask:0xf bound_ctrl:1
	ds_write_b128 v212, v[46:49] offset:672
	ds_write_b128 v212, v[38:41] offset:48
	v_add_f32_dpp v9, v9, v9 row_half_mirror row_mask:0xf bank_mask:0xf bound_ctrl:1
	ds_write_b128 v212, v[14:17] offset:688
	ds_write_b128 v205, v[214:217] offset:1280
	v_mov_b32_e32 v10, 0
	s_branch .Lgdl_sc

; #define LAS __attribute__((address_space(3)))
; __device__ __forceinline__ void gd_task(const Params& p, LAS unsigned char* shm, const int tid, const int s, const int d, const int h, const int rq) {
;     ...
;             for (int ti = 0; ti < ntiles; ++ti) {
;                 const LAS float* ib = inb + (ti & 1) * GD_INF; LAS float* ob = outb + (ti & 1) * GD_OUTF;
;                 LAS float* ow0 = j == 0 ? ob + row : outb + 2 * GD_OUTF + l; const int omask = j == 0 ? -1 : 0;
; #pragma unroll 2
;                 for (int st = 0; st < TT; ++st) {
;                     const LAS float* sb = ib + st * GD_STRIDE;
;                     f32x2 kk[8], qq[8];
; #pragma unroll
;                     for (int e = 0; e < 4; ++e) { const f32x4 a = *(const LAS f32x4*)(sb + 20 * j + 4 * e), b = *(const LAS f32x4*)(sb + 160 + 20 * j + 4 * e);
;                         kk[2 * e] = (f32x2){a[0], a[1]}; kk[2 * e + 1] = (f32x2){a[2], a[3]}; qq[2 * e] = (f32x2){b[0], b[1]}; qq[2 * e + 1] = (f32x2){b[2], b[3]}; }
;                     const float v = sb[320 + row]; const f32x4 sc = *(const LAS f32x4*)(sb + 352); const float wdec = sc[0], cc = sc[1], kq = sc[2], beta = sc[3];
;                     f32x2 pa = sv[0] * kk[0], px = sv[0] * qq[0], pa2 = sv[1] * kk[1], px2 = sv[1] * qq[1];
; #pragma unroll
;                     for (int e = 2; e < 8; e += 2) { pa += sv[e] * kk[e]; px += sv[e] * qq[e]; pa2 += sv[e + 1] * kk[e + 1]; px2 += sv[e + 1] * qq[e + 1]; }
;                     pa += pa2; px += px2;
;                     const float sa = red8(pa[0] + pa[1]), x = red8(px[0] + px[1]);
;                     const float coef = beta * v - cc * sa; const float o = wdec * x + coef * kq;
;                     const f32x2 wd2 = (f32x2){wdec, wdec}, cf2 = (f32x2){coef, coef};
; #pragma unroll
;                     for (int e = 0; e < 8; ++e) sv[e] = sv[e] * wd2 + cf2 * kk[e];
;                     ow0[(st * 32) & omask] = o;
.LBB0_358:
	v_cndmask_b32_e64 v1, 0, 1, s[0:1]
	s_mov_b32 s5, 0xb200
	v_mul_lo_u32 v23, v1, s5
	s_and_b32 s5, s4, 1
	v_lshl_add_u32 v24, s5, 12, v18
	v_add_u32_e32 v1, 0, v23
	v_add_u32_e32 v22, v20, v23
	v_add_u32_e32 v23, v21, v23
	v_cndmask_b32_e32 v24, v19, v24, vcc
	s_mov_b32 s5, 32
	s_mov_b32 s6, 0
	v_mov_b32_e32 v130, v23
	v_mov_b32_e32 v132, v22
	v_mov_b32_e32 v133, v1
	v_mov_b32_e32 v136, v24
	ds_read_b128 v[26:29], v130 offset:0
	ds_read_b128 v[30:33], v130 offset:16
	ds_read_b128 v[34:37], v130 offset:32
	ds_read_b128 v[38:41], v130 offset:48
	ds_read_b128 v[42:45], v130 offset:640
	ds_read_b128 v[46:49], v130 offset:656
	ds_read_b128 v[50:53], v130 offset:672
	ds_read_b128 v[54:57], v130 offset:688
	ds_read_b32 v62, v132 offset:0
	ds_read_b128 v[58:61], v133 offset:1408
	s_waitcnt lgkmcnt(5)
	s_cmp_lt_u32 s4, 2
	s_cbranch_scc1 .Lgd_step_o
	s_cmp_eq_u32 s4, 0x1ff
	s_cbranch_scc1 .Lgd_step_o
.Lgd_step:
	ds_read_b128 v[74:77], v130 offset:1424
	ds_read_b128 v[78:81], v130 offset:1440
	ds_read_b128 v[82:85], v130 offset:1456
	ds_read_b128 v[86:89], v130 offset:1472
	ds_read_b128 v[92:95], v130 offset:2064
	ds_read_b128 v[96:99], v130 offset:2080
	ds_read_b128 v[100:103], v130 offset:2096
	ds_read_b128 v[104:107], v130 offset:2112
	ds_read_b32 v112, v132 offset:1424
	ds_read_b128 v[108:111], v133 offset:2832
	s_waitcnt lgkmcnt(10)
	v_pk_mul_f32 v[64:65], v[2:3], v[26:27]
	v_pk_mul_f32 v[68:69], v[2:3], v[42:43]
	v_pk_fma_f32 v[64:65], v[4:5], v[28:29], v[64:65]
	v_pk_fma_f32 v[68:69], v[4:5], v[44:45], v[68:69]
	v_pk_fma_f32 v[64:65], v[6:7], v[30:31], v[64:65]
	v_pk_fma_f32 v[68:69], v[6:7], v[46:47], v[68:69]
	v_pk_fma_f32 v[64:65], v[8:9], v[32:33], v[64:65]
	v_pk_fma_f32 v[68:69], v[8:9], v[48:49], v[68:69]
	v_pk_fma_f32 v[64:65], v[10:11], v[34:35], v[64:65]
	v_pk_fma_f32 v[68:69], v[10:11], v[50:51], v[68:69]
	v_pk_fma_f32 v[64:65], v[12:13], v[36:37], v[64:65]
	v_pk_fma_f32 v[68:69], v[12:13], v[52:53], v[68:69]
	v_pk_fma_f32 v[64:65], v[14:15], v[38:39], v[64:65]
	v_pk_fma_f32 v[68:69], v[14:15], v[54:55], v[68:69]
	v_pk_fma_f32 v[64:65], v[16:17], v[40:41], v[64:65]
	v_pk_fma_f32 v[68:69], v[16:17], v[56:57], v[68:69]
	v_pk_mul_f32 v[114:115], v[2:3], v[58:59] op_sel_hi:[1,0]
	v_add_f32_e32 v63, v64, v65
	v_add_f32_e32 v72, v68, v69
	v_pk_mul_f32 v[116:117], v[4:5], v[58:59] op_sel_hi:[1,0]
	v_pk_mul_f32 v[118:119], v[6:7], v[58:59] op_sel_hi:[1,0]
	v_add_f32_dpp v63, v63, v63 quad_perm:[1,0,3,2] row_mask:0xf bank_mask:0xf bound_ctrl:1
	v_add_f32_dpp v72, v72, v72 quad_perm:[1,0,3,2] row_mask:0xf bank_mask:0xf bound_ctrl:1
	v_pk_mul_f32 v[120:121], v[8:9], v[58:59] op_sel_hi:[1,0]
	v_add_f32_dpp v63, v63, v63 quad_perm:[2,3,0,1] row_mask:0xf bank_mask:0xf bound_ctrl:1
	v_add_f32_dpp v72, v72, v72 quad_perm:[2,3,0,1] row_mask:0xf bank_mask:0xf bound_ctrl:1
	v_pk_mul_f32 v[122:123], v[10:11], v[58:59] op_sel_hi:[1,0]
	v_add_f32_dpp v63, v63, v63 row_half_mirror row_mask:0xf bank_mask:0xf bound_ctrl:1
	v_add_f32_dpp v72, v72, v72 row_half_mirror row_mask:0xf bank_mask:0xf bound_ctrl:1
	v_pk_mul_f32 v[124:125], v[12:13], v[58:59] op_sel_hi:[1,0]
	v_pk_mul_f32 v[126:127], v[14:15], v[58:59] op_sel_hi:[1,0]
	v_fma_f32 v138, -v63, v59, v62
	v_pk_mul_f32 v[128:129], v[16:17], v[58:59] op_sel_hi:[1,0]
	v_pk_fma_f32 v[2:3], v[26:27], v[138:139], v[114:115] op_sel_hi:[1,0,1]
	v_mul_f32_e32 v113, v138, v60
	v_pk_fma_f32 v[4:5], v[28:29], v[138:139], v[116:117] op_sel_hi:[1,0,1]
	v_pk_fma_f32 v[6:7], v[30:31], v[138:139], v[118:119] op_sel_hi:[1,0,1]
	v_fma_f32 v137, v58, v72, v113
	v_pk_fma_f32 v[8:9], v[32:33], v[138:139], v[120:121] op_sel_hi:[1,0,1]
	v_pk_fma_f32 v[10:11], v[34:35], v[138:139], v[122:123] op_sel_hi:[1,0,1]
	ds_write_b32 v136, v137 offset:0
	v_pk_fma_f32 v[12:13], v[36:37], v[138:139], v[124:125] op_sel_hi:[1,0,1]
	v_pk_fma_f32 v[14:15], v[38:39], v[138:139], v[126:127] op_sel_hi:[1,0,1]
	v_pk_fma_f32 v[16:17], v[40:41], v[138:139], v[128:129] op_sel_hi:[1,0,1]
	ds_read_b128 v[26:29], v130 offset:2848
	ds_read_b128 v[30:33], v130 offset:2864
	ds_read_b128 v[34:37], v130 offset:2880
	ds_read_b128 v[38:41], v130 offset:2896
	ds_read_b128 v[42:45], v130 offset:3488
	ds_read_b128 v[46:49], v130 offset:3504
	ds_read_b128 v[50:53], v130 offset:3520
	ds_read_b128 v[54:57], v130 offset:3536
	ds_read_b32 v62, v132 offset:2848
	ds_read_b128 v[58:61], v133 offset:4256
	s_waitcnt lgkmcnt(10)
; #define LAS __attribute__((address_space(3)))
; __device__ __forceinline__ void gd_task(const Params& p, LAS unsigned char* shm, const int tid, const int s, const int d, const int h, const int rq) {
;     ...
;                 for (int st = 0; st < TT; ++st) {
;                     const LAS float* sb = ib + st * GD_STRIDE;
;                     f32x2 kk[8], qq[8];
; #pragma unroll
;                     for (int e = 0; e < 4; ++e) { const f32x4 a = *(const LAS f32x4*)(sb + 20 * j + 4 * e), b = *(const LAS f32x4*)(sb + 160 + 20 * j + 4 * e);
;                         kk[2 * e] = (f32x2){a[0], a[1]}; kk[2 * e + 1] = (f32x2){a[2], a[3]}; qq[2 * e] = (f32x2){b[0], b[1]}; qq[2 * e + 1] = (f32x2){b[2], b[3]}; }
;                     const float v = sb[320 + row]; const f32x4 sc = *(const LAS f32x4*)(sb + 352); const float wdec = sc[0], cc = sc[1], kq = sc[2], beta = sc[3];
;                     f32x2 pa = sv[0] * kk[0], px = sv[0] * qq[0], pa2 = sv[1] * kk[1], px2 = sv[1] * qq[1];
; #pragma unroll
;                     for (int e = 2; e < 8; e += 2) { pa += sv[e] * kk[e]; px += sv[e] * qq[e]; pa2 += sv[e + 1] * kk[e + 1]; px2 += sv[e + 1] * qq[e + 1]; }
;                     pa += pa2; px += px2;
;                     const float sa = red8(pa[0] + pa[1]), x = red8(px[0] + px[1]);
;                     const float coef = beta * v - cc * sa; const float o = wdec * x + coef * kq;
;                     const f32x2 wd2 = (f32x2){wdec, wdec}, cf2 = (f32x2){coef, coef};
; #pragma unroll
;                     for (int e = 0; e < 8; ++e) sv[e] = sv[e] * wd2 + cf2 * kk[e];
;                     ow0[(st * 32) & omask] = o;
	v_pk_mul_f32 v[64:65], v[2:3], v[74:75]
	v_pk_mul_f32 v[68:69], v[2:3], v[92:93]
	v_pk_fma_f32 v[64:65], v[4:5], v[76:77], v[64:65]
	v_pk_fma_f32 v[68:69], v[4:5], v[94:95], v[68:69]
	v_pk_fma_f32 v[64:65], v[6:7], v[78:79], v[64:65]
	v_pk_fma_f32 v[68:69], v[6:7], v[96:97], v[68:69]
	v_pk_fma_f32 v[64:65], v[8:9], v[80:81], v[64:65]
	v_pk_fma_f32 v[68:69], v[8:9], v[98:99], v[68:69]
	v_pk_fma_f32 v[64:65], v[10:11], v[82:83], v[64:65]
	v_pk_fma_f32 v[68:69], v[10:11], v[100:101], v[68:69]
	v_pk_fma_f32 v[64:65], v[12:13], v[84:85], v[64:65]
	v_pk_fma_f32 v[68:69], v[12:13], v[102:103], v[68:69]
	v_pk_fma_f32 v[64:65], v[14:15], v[86:87], v[64:65]
	v_pk_fma_f32 v[68:69], v[14:15], v[104:105], v[68:69]
	v_pk_fma_f32 v[64:65], v[16:17], v[88:89], v[64:65]
	v_pk_fma_f32 v[68:69], v[16:17], v[106:107], v[68:69]
	v_pk_mul_f32 v[114:115], v[2:3], v[108:109] op_sel_hi:[1,0]
	v_add_f32_e32 v63, v64, v65
	v_add_f32_e32 v72, v68, v69
	v_pk_mul_f32 v[116:117], v[4:5], v[108:109] op_sel_hi:[1,0]
	v_pk_mul_f32 v[118:119], v[6:7], v[108:109] op_sel_hi:[1,0]
	v_add_f32_dpp v63, v63, v63 quad_perm:[1,0,3,2] row_mask:0xf bank_mask:0xf bound_ctrl:1
	v_add_f32_dpp v72, v72, v72 quad_perm:[1,0,3,2] row_mask:0xf bank_mask:0xf bound_ctrl:1
	v_pk_mul_f32 v[120:121], v[8:9], v[108:109] op_sel_hi:[1,0]
	v_add_f32_dpp v63, v63, v63 quad_perm:[2,3,0,1] row_mask:0xf bank_mask:0xf bound_ctrl:1
	v_add_f32_dpp v72, v72, v72 quad_perm:[2,3,0,1] row_mask:0xf bank_mask:0xf bound_ctrl:1
	v_pk_mul_f32 v[122:123], v[10:11], v[108:109] op_sel_hi:[1,0]
	v_add_f32_dpp v63, v63, v63 row_half_mirror row_mask:0xf bank_mask:0xf bound_ctrl:1
	v_add_f32_dpp v72, v72, v72 row_half_mirror row_mask:0xf bank_mask:0xf bound_ctrl:1
	v_pk_mul_f32 v[124:125], v[12:13], v[108:109] op_sel_hi:[1,0]
	v_pk_mul_f32 v[126:127], v[14:15], v[108:109] op_sel_hi:[1,0]
	v_fma_f32 v138, -v63, v109, v112
	v_pk_mul_f32 v[128:129], v[16:17], v[108:109] op_sel_hi:[1,0]
	v_pk_fma_f32 v[2:3], v[74:75], v[138:139], v[114:115] op_sel_hi:[1,0,1]
	v_mul_f32_e32 v113, v138, v110
	v_pk_fma_f32 v[4:5], v[76:77], v[138:139], v[116:117] op_sel_hi:[1,0,1]
	v_pk_fma_f32 v[6:7], v[78:79], v[138:139], v[118:119] op_sel_hi:[1,0,1]
	v_fma_f32 v137, v108, v72, v113
	v_pk_fma_f32 v[8:9], v[80:81], v[138:139], v[120:121] op_sel_hi:[1,0,1]
	v_pk_fma_f32 v[10:11], v[82:83], v[138:139], v[122:123] op_sel_hi:[1,0,1]
	ds_write_b32 v136, v137 offset:128
	v_pk_fma_f32 v[12:13], v[84:85], v[138:139], v[124:125] op_sel_hi:[1,0,1]
	v_pk_fma_f32 v[14:15], v[86:87], v[138:139], v[126:127] op_sel_hi:[1,0,1]
	v_pk_fma_f32 v[16:17], v[88:89], v[138:139], v[128:129] op_sel_hi:[1,0,1]
	ds_read_b128 v[74:77], v130 offset:4272
	ds_read_b128 v[78:81], v130 offset:4288
	ds_read_b128 v[82:85], v130 offset:4304
	ds_read_b128 v[86:89], v130 offset:4320
	ds_read_b128 v[92:95], v130 offset:4912
	ds_read_b128 v[96:99], v130 offset:4928
	ds_read_b128 v[100:103], v130 offset:4944
	ds_read_b128 v[104:107], v130 offset:4960
	ds_read_b32 v112, v132 offset:4272
	ds_read_b128 v[108:111], v133 offset:5680
	s_waitcnt lgkmcnt(10)
	v_pk_mul_f32 v[64:65], v[2:3], v[26:27]
	v_pk_mul_f32 v[68:69], v[2:3], v[42:43]
	v_pk_fma_f32 v[64:65], v[4:5], v[28:29], v[64:65]
	v_pk_fma_f32 v[68:69], v[4:5], v[44:45], v[68:69]
	v_pk_fma_f32 v[64:65], v[6:7], v[30:31], v[64:65]
	v_pk_fma_f32 v[68:69], v[6:7], v[46:47], v[68:69]
	v_pk_fma_f32 v[64:65], v[8:9], v[32:33], v[64:65]
	v_pk_fma_f32 v[68:69], v[8:9], v[48:49], v[68:69]
	v_pk_fma_f32 v[64:65], v[10:11], v[34:35], v[64:65]
	v_pk_fma_f32 v[68:69], v[10:11], v[50:51], v[68:69]
	v_pk_fma_f32 v[64:65], v[12:13], v[36:37], v[64:65]
	v_pk_fma_f32 v[68:69], v[12:13], v[52:53], v[68:69]
	v_pk_fma_f32 v[64:65], v[14:15], v[38:39], v[64:65]
	v_pk_fma_f32 v[68:69], v[14:15], v[54:55], v[68:69]
	v_pk_fma_f32 v[64:65], v[16:17], v[40:41], v[64:65]
	v_pk_fma_f32 v[68:69], v[16:17], v[56:57], v[68:69]
	v_pk_mul_f32 v[114:115], v[2:3], v[58:59] op_sel_hi:[1,0]
	v_add_f32_e32 v63, v64, v65
	v_add_f32_e32 v72, v68, v69
	v_pk_mul_f32 v[116:117], v[4:5], v[58:59] op_sel_hi:[1,0]
	v_pk_mul_f32 v[118:119], v[6:7], v[58:59] op_sel_hi:[1,0]
	v_add_f32_dpp v63, v63, v63 quad_perm:[1,0,3,2] row_mask:0xf bank_mask:0xf bound_ctrl:1
	v_add_f32_dpp v72, v72, v72 quad_perm:[1,0,3,2] row_mask:0xf bank_mask:0xf bound_ctrl:1
	v_pk_mul_f32 v[120:121], v[8:9], v[58:59] op_sel_hi:[1,0]
	v_add_f32_dpp v63, v63, v63 quad_perm:[2,3,0,1] row_mask:0xf bank_mask:0xf bound_ctrl:1
	v_add_f32_dpp v72, v72, v72 quad_perm:[2,3,0,1] row_mask:0xf bank_mask:0xf bound_ctrl:1
	v_pk_mul_f32 v[122:123], v[10:11], v[58:59] op_sel_hi:[1,0]
	v_add_f32_dpp v63, v63, v63 row_half_mirror row_mask:0xf bank_mask:0xf bound_ctrl:1
	v_add_f32_dpp v72, v72, v72 row_half_mirror row_mask:0xf bank_mask:0xf bound_ctrl:1
	v_pk_mul_f32 v[124:125], v[12:13], v[58:59] op_sel_hi:[1,0]
	v_pk_mul_f32 v[126:127], v[14:15], v[58:59] op_sel_hi:[1,0]
	v_fma_f32 v138, -v63, v59, v62
	v_pk_mul_f32 v[128:129], v[16:17], v[58:59] op_sel_hi:[1,0]
	v_pk_fma_f32 v[2:3], v[26:27], v[138:139], v[114:115] op_sel_hi:[1,0,1]
	v_mul_f32_e32 v113, v138, v60
	v_pk_fma_f32 v[4:5], v[28:29], v[138:139], v[116:117] op_sel_hi:[1,0,1]
	v_pk_fma_f32 v[6:7], v[30:31], v[138:139], v[118:119] op_sel_hi:[1,0,1]
	v_fma_f32 v137, v58, v72, v113
	v_pk_fma_f32 v[8:9], v[32:33], v[138:139], v[120:121] op_sel_hi:[1,0,1]
	v_pk_fma_f32 v[10:11], v[34:35], v[138:139], v[122:123] op_sel_hi:[1,0,1]
	ds_write_b32 v136, v137 offset:256
	v_pk_fma_f32 v[12:13], v[36:37], v[138:139], v[124:125] op_sel_hi:[1,0,1]
	v_pk_fma_f32 v[14:15], v[38:39], v[138:139], v[126:127] op_sel_hi:[1,0,1]
	v_pk_fma_f32 v[16:17], v[40:41], v[138:139], v[128:129] op_sel_hi:[1,0,1]
	ds_read_b128 v[26:29], v130 offset:5696
	ds_read_b128 v[30:33], v130 offset:5712
	ds_read_b128 v[34:37], v130 offset:5728
	ds_read_b128 v[38:41], v130 offset:5744
	ds_read_b128 v[42:45], v130 offset:6336
	ds_read_b128 v[46:49], v130 offset:6352
	ds_read_b128 v[50:53], v130 offset:6368
	ds_read_b128 v[54:57], v130 offset:6384
	ds_read_b32 v62, v132 offset:5696
	ds_read_b128 v[58:61], v133 offset:7104
	s_waitcnt lgkmcnt(10)
; #define LAS __attribute__((address_space(3)))
; __device__ __forceinline__ void gd_task(const Params& p, LAS unsigned char* shm, const int tid, const int s, const int d, const int h, const int rq) {
;     ...
;                 for (int st = 0; st < TT; ++st) {
;                     const LAS float* sb = ib + st * GD_STRIDE;
;                     f32x2 kk[8], qq[8];
; #pragma unroll
;                     for (int e = 0; e < 4; ++e) { const f32x4 a = *(const LAS f32x4*)(sb + 20 * j + 4 * e), b = *(const LAS f32x4*)(sb + 160 + 20 * j + 4 * e);
;                         kk[2 * e] = (f32x2){a[0], a[1]}; kk[2 * e + 1] = (f32x2){a[2], a[3]}; qq[2 * e] = (f32x2){b[0], b[1]}; qq[2 * e + 1] = (f32x2){b[2], b[3]}; }
;                     const float v = sb[320 + row]; const f32x4 sc = *(const LAS f32x4*)(sb + 352); const float wdec = sc[0], cc = sc[1], kq = sc[2], beta = sc[3];
;                     f32x2 pa = sv[0] * kk[0], px = sv[0] * qq[0], pa2 = sv[1] * kk[1], px2 = sv[1] * qq[1];
; #pragma unroll
;                     for (int e = 2; e < 8; e += 2) { pa += sv[e] * kk[e]; px += sv[e] * qq[e]; pa2 += sv[e + 1] * kk[e + 1]; px2 += sv[e + 1] * qq[e + 1]; }
;                     pa += pa2; px += px2;
;                     const float sa = red8(pa[0] + pa[1]), x = red8(px[0] + px[1]);
;                     const float coef = beta * v - cc * sa; const float o = wdec * x + coef * kq;
;                     const f32x2 wd2 = (f32x2){wdec, wdec}, cf2 = (f32x2){coef, coef};
; #pragma unroll
;                     for (int e = 0; e < 8; ++e) sv[e] = sv[e] * wd2 + cf2 * kk[e];
;                     ow0[(st * 32) & omask] = o;
	v_pk_mul_f32 v[64:65], v[2:3], v[74:75]
	v_pk_mul_f32 v[68:69], v[2:3], v[92:93]
	v_pk_fma_f32 v[64:65], v[4:5], v[76:77], v[64:65]
	v_pk_fma_f32 v[68:69], v[4:5], v[94:95], v[68:69]
	v_pk_fma_f32 v[64:65], v[6:7], v[78:79], v[64:65]
	v_pk_fma_f32 v[68:69], v[6:7], v[96:97], v[68:69]
	v_pk_fma_f32 v[64:65], v[8:9], v[80:81], v[64:65]
	v_pk_fma_f32 v[68:69], v[8:9], v[98:99], v[68:69]
	v_pk_fma_f32 v[64:65], v[10:11], v[82:83], v[64:65]
	v_pk_fma_f32 v[68:69], v[10:11], v[100:101], v[68:69]
	v_pk_fma_f32 v[64:65], v[12:13], v[84:85], v[64:65]
	v_pk_fma_f32 v[68:69], v[12:13], v[102:103], v[68:69]
	v_pk_fma_f32 v[64:65], v[14:15], v[86:87], v[64:65]
	v_pk_fma_f32 v[68:69], v[14:15], v[104:105], v[68:69]
	v_pk_fma_f32 v[64:65], v[16:17], v[88:89], v[64:65]
	v_pk_fma_f32 v[68:69], v[16:17], v[106:107], v[68:69]
	v_pk_mul_f32 v[114:115], v[2:3], v[108:109] op_sel_hi:[1,0]
	v_add_f32_e32 v63, v64, v65
	v_add_f32_e32 v72, v68, v69
	v_pk_mul_f32 v[116:117], v[4:5], v[108:109] op_sel_hi:[1,0]
	v_pk_mul_f32 v[118:119], v[6:7], v[108:109] op_sel_hi:[1,0]
	v_add_f32_dpp v63, v63, v63 quad_perm:[1,0,3,2] row_mask:0xf bank_mask:0xf bound_ctrl:1
	v_add_f32_dpp v72, v72, v72 quad_perm:[1,0,3,2] row_mask:0xf bank_mask:0xf bound_ctrl:1
	v_pk_mul_f32 v[120:121], v[8:9], v[108:109] op_sel_hi:[1,0]
	v_add_f32_dpp v63, v63, v63 quad_perm:[2,3,0,1] row_mask:0xf bank_mask:0xf bound_ctrl:1
	v_add_f32_dpp v72, v72, v72 quad_perm:[2,3,0,1] row_mask:0xf bank_mask:0xf bound_ctrl:1
	v_pk_mul_f32 v[122:123], v[10:11], v[108:109] op_sel_hi:[1,0]
	v_add_f32_dpp v63, v63, v63 row_half_mirror row_mask:0xf bank_mask:0xf bound_ctrl:1
	v_add_f32_dpp v72, v72, v72 row_half_mirror row_mask:0xf bank_mask:0xf bound_ctrl:1
	v_pk_mul_f32 v[124:125], v[12:13], v[108:109] op_sel_hi:[1,0]
	v_pk_mul_f32 v[126:127], v[14:15], v[108:109] op_sel_hi:[1,0]
	v_fma_f32 v138, -v63, v109, v112
	v_pk_mul_f32 v[128:129], v[16:17], v[108:109] op_sel_hi:[1,0]
	v_pk_fma_f32 v[2:3], v[74:75], v[138:139], v[114:115] op_sel_hi:[1,0,1]
	v_mul_f32_e32 v113, v138, v110
	v_pk_fma_f32 v[4:5], v[76:77], v[138:139], v[116:117] op_sel_hi:[1,0,1]
	v_pk_fma_f32 v[6:7], v[78:79], v[138:139], v[118:119] op_sel_hi:[1,0,1]
	v_fma_f32 v137, v108, v72, v113
	v_pk_fma_f32 v[8:9], v[80:81], v[138:139], v[120:121] op_sel_hi:[1,0,1]
	v_pk_fma_f32 v[10:11], v[82:83], v[138:139], v[122:123] op_sel_hi:[1,0,1]
	ds_write_b32 v136, v137 offset:384
	v_pk_fma_f32 v[12:13], v[84:85], v[138:139], v[124:125] op_sel_hi:[1,0,1]
	v_pk_fma_f32 v[14:15], v[86:87], v[138:139], v[126:127] op_sel_hi:[1,0,1]
	v_pk_fma_f32 v[16:17], v[88:89], v[138:139], v[128:129] op_sel_hi:[1,0,1]
	ds_read_b128 v[74:77], v130 offset:7120
	ds_read_b128 v[78:81], v130 offset:7136
	ds_read_b128 v[82:85], v130 offset:7152
	ds_read_b128 v[86:89], v130 offset:7168
	ds_read_b128 v[92:95], v130 offset:7760
	ds_read_b128 v[96:99], v130 offset:7776
	ds_read_b128 v[100:103], v130 offset:7792
	ds_read_b128 v[104:107], v130 offset:7808
	ds_read_b32 v112, v132 offset:7120
	ds_read_b128 v[108:111], v133 offset:8528
	s_waitcnt lgkmcnt(10)
	v_pk_mul_f32 v[64:65], v[2:3], v[26:27]
	v_pk_mul_f32 v[68:69], v[2:3], v[42:43]
	v_pk_fma_f32 v[64:65], v[4:5], v[28:29], v[64:65]
	v_pk_fma_f32 v[68:69], v[4:5], v[44:45], v[68:69]
	v_pk_fma_f32 v[64:65], v[6:7], v[30:31], v[64:65]
	v_pk_fma_f32 v[68:69], v[6:7], v[46:47], v[68:69]
	v_pk_fma_f32 v[64:65], v[8:9], v[32:33], v[64:65]
	v_pk_fma_f32 v[68:69], v[8:9], v[48:49], v[68:69]
	v_pk_fma_f32 v[64:65], v[10:11], v[34:35], v[64:65]
	v_pk_fma_f32 v[68:69], v[10:11], v[50:51], v[68:69]
	v_pk_fma_f32 v[64:65], v[12:13], v[36:37], v[64:65]
	v_pk_fma_f32 v[68:69], v[12:13], v[52:53], v[68:69]
	v_pk_fma_f32 v[64:65], v[14:15], v[38:39], v[64:65]
	v_pk_fma_f32 v[68:69], v[14:15], v[54:55], v[68:69]
	v_pk_fma_f32 v[64:65], v[16:17], v[40:41], v[64:65]
	v_pk_fma_f32 v[68:69], v[16:17], v[56:57], v[68:69]
	v_pk_mul_f32 v[114:115], v[2:3], v[58:59] op_sel_hi:[1,0]
	v_add_f32_e32 v63, v64, v65
	v_add_f32_e32 v72, v68, v69
	v_pk_mul_f32 v[116:117], v[4:5], v[58:59] op_sel_hi:[1,0]
	v_pk_mul_f32 v[118:119], v[6:7], v[58:59] op_sel_hi:[1,0]
	v_add_f32_dpp v63, v63, v63 quad_perm:[1,0,3,2] row_mask:0xf bank_mask:0xf bound_ctrl:1
	v_add_f32_dpp v72, v72, v72 quad_perm:[1,0,3,2] row_mask:0xf bank_mask:0xf bound_ctrl:1
	v_pk_mul_f32 v[120:121], v[8:9], v[58:59] op_sel_hi:[1,0]
	v_add_f32_dpp v63, v63, v63 quad_perm:[2,3,0,1] row_mask:0xf bank_mask:0xf bound_ctrl:1
	v_add_f32_dpp v72, v72, v72 quad_perm:[2,3,0,1] row_mask:0xf bank_mask:0xf bound_ctrl:1
	v_pk_mul_f32 v[122:123], v[10:11], v[58:59] op_sel_hi:[1,0]
	v_add_f32_dpp v63, v63, v63 row_half_mirror row_mask:0xf bank_mask:0xf bound_ctrl:1
	v_add_f32_dpp v72, v72, v72 row_half_mirror row_mask:0xf bank_mask:0xf bound_ctrl:1
	v_pk_mul_f32 v[124:125], v[12:13], v[58:59] op_sel_hi:[1,0]
	v_pk_mul_f32 v[126:127], v[14:15], v[58:59] op_sel_hi:[1,0]
	v_fma_f32 v138, -v63, v59, v62
	v_pk_mul_f32 v[128:129], v[16:17], v[58:59] op_sel_hi:[1,0]
	v_pk_fma_f32 v[2:3], v[26:27], v[138:139], v[114:115] op_sel_hi:[1,0,1]
	v_mul_f32_e32 v113, v138, v60
	v_pk_fma_f32 v[4:5], v[28:29], v[138:139], v[116:117] op_sel_hi:[1,0,1]
	v_pk_fma_f32 v[6:7], v[30:31], v[138:139], v[118:119] op_sel_hi:[1,0,1]
	v_fma_f32 v137, v58, v72, v113
	v_pk_fma_f32 v[8:9], v[32:33], v[138:139], v[120:121] op_sel_hi:[1,0,1]
	v_pk_fma_f32 v[10:11], v[34:35], v[138:139], v[122:123] op_sel_hi:[1,0,1]
	ds_write_b32 v136, v137 offset:512
	v_pk_fma_f32 v[12:13], v[36:37], v[138:139], v[124:125] op_sel_hi:[1,0,1]
	v_pk_fma_f32 v[14:15], v[38:39], v[138:139], v[126:127] op_sel_hi:[1,0,1]
	v_pk_fma_f32 v[16:17], v[40:41], v[138:139], v[128:129] op_sel_hi:[1,0,1]
	ds_read_b128 v[26:29], v130 offset:8544
	ds_read_b128 v[30:33], v130 offset:8560
	ds_read_b128 v[34:37], v130 offset:8576
	ds_read_b128 v[38:41], v130 offset:8592
	ds_read_b128 v[42:45], v130 offset:9184
	ds_read_b128 v[46:49], v130 offset:9200
	ds_read_b128 v[50:53], v130 offset:9216
	ds_read_b128 v[54:57], v130 offset:9232
	ds_read_b32 v62, v132 offset:8544
	ds_read_b128 v[58:61], v133 offset:9952
	s_waitcnt lgkmcnt(10)
; #define LAS __attribute__((address_space(3)))
; __device__ __forceinline__ void gd_task(const Params& p, LAS unsigned char* shm, const int tid, const int s, const int d, const int h, const int rq) {
;     ...
;                 for (int st = 0; st < TT; ++st) {
;                     const LAS float* sb = ib + st * GD_STRIDE;
;                     f32x2 kk[8], qq[8];
; #pragma unroll
;                     for (int e = 0; e < 4; ++e) { const f32x4 a = *(const LAS f32x4*)(sb + 20 * j + 4 * e), b = *(const LAS f32x4*)(sb + 160 + 20 * j + 4 * e);
;                         kk[2 * e] = (f32x2){a[0], a[1]}; kk[2 * e + 1] = (f32x2){a[2], a[3]}; qq[2 * e] = (f32x2){b[0], b[1]}; qq[2 * e + 1] = (f32x2){b[2], b[3]}; }
;                     const float v = sb[320 + row]; const f32x4 sc = *(const LAS f32x4*)(sb + 352); const float wdec = sc[0], cc = sc[1], kq = sc[2], beta = sc[3];
;                     f32x2 pa = sv[0] * kk[0], px = sv[0] * qq[0], pa2 = sv[1] * kk[1], px2 = sv[1] * qq[1];
; #pragma unroll
;                     for (int e = 2; e < 8; e += 2) { pa += sv[e] * kk[e]; px += sv[e] * qq[e]; pa2 += sv[e + 1] * kk[e + 1]; px2 += sv[e + 1] * qq[e + 1]; }
;                     pa += pa2; px += px2;
;                     const float sa = red8(pa[0] + pa[1]), x = red8(px[0] + px[1]);
;                     const float coef = beta * v - cc * sa; const float o = wdec * x + coef * kq;
;                     const f32x2 wd2 = (f32x2){wdec, wdec}, cf2 = (f32x2){coef, coef};
; #pragma unroll
;                     for (int e = 0; e < 8; ++e) sv[e] = sv[e] * wd2 + cf2 * kk[e];
;                     ow0[(st * 32) & omask] = o;
	v_pk_mul_f32 v[64:65], v[2:3], v[74:75]
	v_pk_mul_f32 v[68:69], v[2:3], v[92:93]
	v_pk_fma_f32 v[64:65], v[4:5], v[76:77], v[64:65]
	v_pk_fma_f32 v[68:69], v[4:5], v[94:95], v[68:69]
	v_pk_fma_f32 v[64:65], v[6:7], v[78:79], v[64:65]
	v_pk_fma_f32 v[68:69], v[6:7], v[96:97], v[68:69]
	v_pk_fma_f32 v[64:65], v[8:9], v[80:81], v[64:65]
	v_pk_fma_f32 v[68:69], v[8:9], v[98:99], v[68:69]
	v_pk_fma_f32 v[64:65], v[10:11], v[82:83], v[64:65]
	v_pk_fma_f32 v[68:69], v[10:11], v[100:101], v[68:69]
	v_pk_fma_f32 v[64:65], v[12:13], v[84:85], v[64:65]
	v_pk_fma_f32 v[68:69], v[12:13], v[102:103], v[68:69]
	v_pk_fma_f32 v[64:65], v[14:15], v[86:87], v[64:65]
	v_pk_fma_f32 v[68:69], v[14:15], v[104:105], v[68:69]
	v_pk_fma_f32 v[64:65], v[16:17], v[88:89], v[64:65]
	v_pk_fma_f32 v[68:69], v[16:17], v[106:107], v[68:69]
	v_pk_mul_f32 v[114:115], v[2:3], v[108:109] op_sel_hi:[1,0]
	v_add_f32_e32 v63, v64, v65
	v_add_f32_e32 v72, v68, v69
	v_pk_mul_f32 v[116:117], v[4:5], v[108:109] op_sel_hi:[1,0]
	v_pk_mul_f32 v[118:119], v[6:7], v[108:109] op_sel_hi:[1,0]
	v_add_f32_dpp v63, v63, v63 quad_perm:[1,0,3,2] row_mask:0xf bank_mask:0xf bound_ctrl:1
	v_add_f32_dpp v72, v72, v72 quad_perm:[1,0,3,2] row_mask:0xf bank_mask:0xf bound_ctrl:1
	v_pk_mul_f32 v[120:121], v[8:9], v[108:109] op_sel_hi:[1,0]
	v_add_f32_dpp v63, v63, v63 quad_perm:[2,3,0,1] row_mask:0xf bank_mask:0xf bound_ctrl:1
	v_add_f32_dpp v72, v72, v72 quad_perm:[2,3,0,1] row_mask:0xf bank_mask:0xf bound_ctrl:1
	v_pk_mul_f32 v[122:123], v[10:11], v[108:109] op_sel_hi:[1,0]
	v_add_f32_dpp v63, v63, v63 row_half_mirror row_mask:0xf bank_mask:0xf bound_ctrl:1
	v_add_f32_dpp v72, v72, v72 row_half_mirror row_mask:0xf bank_mask:0xf bound_ctrl:1
	v_pk_mul_f32 v[124:125], v[12:13], v[108:109] op_sel_hi:[1,0]
	v_pk_mul_f32 v[126:127], v[14:15], v[108:109] op_sel_hi:[1,0]
	v_fma_f32 v138, -v63, v109, v112
	v_pk_mul_f32 v[128:129], v[16:17], v[108:109] op_sel_hi:[1,0]
	v_pk_fma_f32 v[2:3], v[74:75], v[138:139], v[114:115] op_sel_hi:[1,0,1]
	v_mul_f32_e32 v113, v138, v110
	v_pk_fma_f32 v[4:5], v[76:77], v[138:139], v[116:117] op_sel_hi:[1,0,1]
	v_pk_fma_f32 v[6:7], v[78:79], v[138:139], v[118:119] op_sel_hi:[1,0,1]
	v_fma_f32 v137, v108, v72, v113
	v_pk_fma_f32 v[8:9], v[80:81], v[138:139], v[120:121] op_sel_hi:[1,0,1]
	v_pk_fma_f32 v[10:11], v[82:83], v[138:139], v[122:123] op_sel_hi:[1,0,1]
	ds_write_b32 v136, v137 offset:640
	v_pk_fma_f32 v[12:13], v[84:85], v[138:139], v[124:125] op_sel_hi:[1,0,1]
	v_pk_fma_f32 v[14:15], v[86:87], v[138:139], v[126:127] op_sel_hi:[1,0,1]
	v_pk_fma_f32 v[16:17], v[88:89], v[138:139], v[128:129] op_sel_hi:[1,0,1]
	ds_read_b128 v[74:77], v130 offset:9968
	ds_read_b128 v[78:81], v130 offset:9984
	ds_read_b128 v[82:85], v130 offset:10000
	ds_read_b128 v[86:89], v130 offset:10016
	ds_read_b128 v[92:95], v130 offset:10608
	ds_read_b128 v[96:99], v130 offset:10624
	ds_read_b128 v[100:103], v130 offset:10640
	ds_read_b128 v[104:107], v130 offset:10656
	ds_read_b32 v112, v132 offset:9968
	ds_read_b128 v[108:111], v133 offset:11376
	s_waitcnt lgkmcnt(10)
; #define LAS __attribute__((address_space(3)))
; __device__ __forceinline__ void gd_task(const Params& p, LAS unsigned char* shm, const int tid, const int s, const int d, const int h, const int rq) {
;     ...
;                 for (int st = 0; st < TT; ++st) {
;                     const LAS float* sb = ib + st * GD_STRIDE;
;                     f32x2 kk[8], qq[8];
; #pragma unroll
;                     for (int e = 0; e < 4; ++e) { const f32x4 a = *(const LAS f32x4*)(sb + 20 * j + 4 * e), b = *(const LAS f32x4*)(sb + 160 + 20 * j + 4 * e);
;                         kk[2 * e] = (f32x2){a[0], a[1]}; kk[2 * e + 1] = (f32x2){a[2], a[3]}; qq[2 * e] = (f32x2){b[0], b[1]}; qq[2 * e + 1] = (f32x2){b[2], b[3]}; }
;                     const float v = sb[320 + row]; const f32x4 sc = *(const LAS f32x4*)(sb + 352); const float wdec = sc[0], cc = sc[1], kq = sc[2], beta = sc[3];
;                     f32x2 pa = sv[0] * kk[0], px = sv[0] * qq[0], pa2 = sv[1] * kk[1], px2 = sv[1] * qq[1];
; #pragma unroll
;                     for (int e = 2; e < 8; e += 2) { pa += sv[e] * kk[e]; px += sv[e] * qq[e]; pa2 += sv[e + 1] * kk[e + 1]; px2 += sv[e + 1] * qq[e + 1]; }
;                     pa += pa2; px += px2;
;                     const float sa = red8(pa[0] + pa[1]), x = red8(px[0] + px[1]);
;                     const float coef = beta * v - cc * sa; const float o = wdec * x + coef * kq;
;                     const f32x2 wd2 = (f32x2){wdec, wdec}, cf2 = (f32x2){coef, coef};
; #pragma unroll
;                     for (int e = 0; e < 8; ++e) sv[e] = sv[e] * wd2 + cf2 * kk[e];
;                     ow0[(st * 32) & omask] = o;
	v_pk_mul_f32 v[64:65], v[2:3], v[26:27]
	v_pk_mul_f32 v[68:69], v[2:3], v[42:43]
	v_pk_fma_f32 v[64:65], v[4:5], v[28:29], v[64:65]
	v_pk_fma_f32 v[68:69], v[4:5], v[44:45], v[68:69]
	v_pk_fma_f32 v[64:65], v[6:7], v[30:31], v[64:65]
	v_pk_fma_f32 v[68:69], v[6:7], v[46:47], v[68:69]
	v_pk_fma_f32 v[64:65], v[8:9], v[32:33], v[64:65]
	v_pk_fma_f32 v[68:69], v[8:9], v[48:49], v[68:69]
	v_pk_fma_f32 v[64:65], v[10:11], v[34:35], v[64:65]
	v_pk_fma_f32 v[68:69], v[10:11], v[50:51], v[68:69]
	v_pk_fma_f32 v[64:65], v[12:13], v[36:37], v[64:65]
	v_pk_fma_f32 v[68:69], v[12:13], v[52:53], v[68:69]
	v_pk_fma_f32 v[64:65], v[14:15], v[38:39], v[64:65]
	v_pk_fma_f32 v[68:69], v[14:15], v[54:55], v[68:69]
	v_pk_fma_f32 v[64:65], v[16:17], v[40:41], v[64:65]
	v_pk_fma_f32 v[68:69], v[16:17], v[56:57], v[68:69]
	v_pk_mul_f32 v[114:115], v[2:3], v[58:59] op_sel_hi:[1,0]
	v_add_f32_e32 v63, v64, v65
	v_add_f32_e32 v72, v68, v69
	v_pk_mul_f32 v[116:117], v[4:5], v[58:59] op_sel_hi:[1,0]
	v_pk_mul_f32 v[118:119], v[6:7], v[58:59] op_sel_hi:[1,0]
	v_add_f32_dpp v63, v63, v63 quad_perm:[1,0,3,2] row_mask:0xf bank_mask:0xf bound_ctrl:1
	v_add_f32_dpp v72, v72, v72 quad_perm:[1,0,3,2] row_mask:0xf bank_mask:0xf bound_ctrl:1
	v_pk_mul_f32 v[120:121], v[8:9], v[58:59] op_sel_hi:[1,0]
	v_add_f32_dpp v63, v63, v63 quad_perm:[2,3,0,1] row_mask:0xf bank_mask:0xf bound_ctrl:1
	v_add_f32_dpp v72, v72, v72 quad_perm:[2,3,0,1] row_mask:0xf bank_mask:0xf bound_ctrl:1
	v_pk_mul_f32 v[122:123], v[10:11], v[58:59] op_sel_hi:[1,0]
	v_add_f32_dpp v63, v63, v63 row_half_mirror row_mask:0xf bank_mask:0xf bound_ctrl:1
	v_add_f32_dpp v72, v72, v72 row_half_mirror row_mask:0xf bank_mask:0xf bound_ctrl:1
	v_pk_mul_f32 v[124:125], v[12:13], v[58:59] op_sel_hi:[1,0]
	v_pk_mul_f32 v[126:127], v[14:15], v[58:59] op_sel_hi:[1,0]
	v_fma_f32 v138, -v63, v59, v62
	v_pk_mul_f32 v[128:129], v[16:17], v[58:59] op_sel_hi:[1,0]
	v_pk_fma_f32 v[2:3], v[26:27], v[138:139], v[114:115] op_sel_hi:[1,0,1]
	v_mul_f32_e32 v113, v138, v60
	v_pk_fma_f32 v[4:5], v[28:29], v[138:139], v[116:117] op_sel_hi:[1,0,1]
	v_pk_fma_f32 v[6:7], v[30:31], v[138:139], v[118:119] op_sel_hi:[1,0,1]
	v_fma_f32 v137, v58, v72, v113
	v_pk_fma_f32 v[8:9], v[32:33], v[138:139], v[120:121] op_sel_hi:[1,0,1]
	v_pk_fma_f32 v[10:11], v[34:35], v[138:139], v[122:123] op_sel_hi:[1,0,1]
	ds_write_b32 v136, v137 offset:768
	v_pk_fma_f32 v[12:13], v[36:37], v[138:139], v[124:125] op_sel_hi:[1,0,1]
	v_pk_fma_f32 v[14:15], v[38:39], v[138:139], v[126:127] op_sel_hi:[1,0,1]
	v_pk_fma_f32 v[16:17], v[40:41], v[138:139], v[128:129] op_sel_hi:[1,0,1]
	ds_read_b128 v[26:29], v130 offset:11392
	ds_read_b128 v[30:33], v130 offset:11408
	ds_read_b128 v[34:37], v130 offset:11424
	ds_read_b128 v[38:41], v130 offset:11440
	ds_read_b128 v[42:45], v130 offset:12032
	ds_read_b128 v[46:49], v130 offset:12048
	ds_read_b128 v[50:53], v130 offset:12064
	ds_read_b128 v[54:57], v130 offset:12080
	ds_read_b32 v62, v132 offset:11392
	ds_read_b128 v[58:61], v133 offset:12800
	s_waitcnt lgkmcnt(10)
	v_pk_mul_f32 v[64:65], v[2:3], v[74:75]
	v_pk_mul_f32 v[68:69], v[2:3], v[92:93]
	v_pk_fma_f32 v[64:65], v[4:5], v[76:77], v[64:65]
	v_pk_fma_f32 v[68:69], v[4:5], v[94:95], v[68:69]
	v_pk_fma_f32 v[64:65], v[6:7], v[78:79], v[64:65]
	v_pk_fma_f32 v[68:69], v[6:7], v[96:97], v[68:69]
	v_pk_fma_f32 v[64:65], v[8:9], v[80:81], v[64:65]
	v_pk_fma_f32 v[68:69], v[8:9], v[98:99], v[68:69]
	v_pk_fma_f32 v[64:65], v[10:11], v[82:83], v[64:65]
	v_pk_fma_f32 v[68:69], v[10:11], v[100:101], v[68:69]
	v_pk_fma_f32 v[64:65], v[12:13], v[84:85], v[64:65]
	v_pk_fma_f32 v[68:69], v[12:13], v[102:103], v[68:69]
	v_pk_fma_f32 v[64:65], v[14:15], v[86:87], v[64:65]
	v_pk_fma_f32 v[68:69], v[14:15], v[104:105], v[68:69]
	v_pk_fma_f32 v[64:65], v[16:17], v[88:89], v[64:65]
	v_pk_fma_f32 v[68:69], v[16:17], v[106:107], v[68:69]
	v_pk_mul_f32 v[114:115], v[2:3], v[108:109] op_sel_hi:[1,0]
	v_add_f32_e32 v63, v64, v65
	v_add_f32_e32 v72, v68, v69
	v_pk_mul_f32 v[116:117], v[4:5], v[108:109] op_sel_hi:[1,0]
	v_pk_mul_f32 v[118:119], v[6:7], v[108:109] op_sel_hi:[1,0]
	v_add_f32_dpp v63, v63, v63 quad_perm:[1,0,3,2] row_mask:0xf bank_mask:0xf bound_ctrl:1
	v_add_f32_dpp v72, v72, v72 quad_perm:[1,0,3,2] row_mask:0xf bank_mask:0xf bound_ctrl:1
	v_pk_mul_f32 v[120:121], v[8:9], v[108:109] op_sel_hi:[1,0]
	v_add_f32_dpp v63, v63, v63 quad_perm:[2,3,0,1] row_mask:0xf bank_mask:0xf bound_ctrl:1
	v_add_f32_dpp v72, v72, v72 quad_perm:[2,3,0,1] row_mask:0xf bank_mask:0xf bound_ctrl:1
	v_pk_mul_f32 v[122:123], v[10:11], v[108:109] op_sel_hi:[1,0]
	v_add_f32_dpp v63, v63, v63 row_half_mirror row_mask:0xf bank_mask:0xf bound_ctrl:1
	v_add_f32_dpp v72, v72, v72 row_half_mirror row_mask:0xf bank_mask:0xf bound_ctrl:1
	v_pk_mul_f32 v[124:125], v[12:13], v[108:109] op_sel_hi:[1,0]
	v_pk_mul_f32 v[126:127], v[14:15], v[108:109] op_sel_hi:[1,0]
	v_fma_f32 v138, -v63, v109, v112
	v_pk_mul_f32 v[128:129], v[16:17], v[108:109] op_sel_hi:[1,0]
	v_pk_fma_f32 v[2:3], v[74:75], v[138:139], v[114:115] op_sel_hi:[1,0,1]
	v_mul_f32_e32 v113, v138, v110
	v_pk_fma_f32 v[4:5], v[76:77], v[138:139], v[116:117] op_sel_hi:[1,0,1]
	v_pk_fma_f32 v[6:7], v[78:79], v[138:139], v[118:119] op_sel_hi:[1,0,1]
	v_fma_f32 v137, v108, v72, v113
	v_pk_fma_f32 v[8:9], v[80:81], v[138:139], v[120:121] op_sel_hi:[1,0,1]
	v_pk_fma_f32 v[10:11], v[82:83], v[138:139], v[122:123] op_sel_hi:[1,0,1]
	ds_write_b32 v136, v137 offset:896
	v_pk_fma_f32 v[12:13], v[84:85], v[138:139], v[124:125] op_sel_hi:[1,0,1]
	v_pk_fma_f32 v[14:15], v[86:87], v[138:139], v[126:127] op_sel_hi:[1,0,1]
	v_pk_fma_f32 v[16:17], v[88:89], v[138:139], v[128:129] op_sel_hi:[1,0,1]
	v_add_u32_e32 v130, 0x2c80, v130
	v_add_u32_e32 v132, 0x2c80, v132
	v_add_u32_e32 v133, 0x2c80, v133
	v_add_u32_e32 v136, 0x400, v136
	s_add_i32 s6, s6, 1
	s_cmp_eq_u32 s6, 4
	s_cbranch_scc0 .Lgd_step
	s_branch .Lgd_done

; #define LAS __attribute__((address_space(3)))
; __device__ __forceinline__ void gd_task(const Params& p, LAS unsigned char* shm, const int tid, const int s, const int d, const int h, const int rq) {
;     ...
;             for (int ti = 0; ti < ntiles; ++ti) {
;                 const LAS float* ib = inb + (ti & 1) * GD_INF; LAS float* ob = outb + (ti & 1) * GD_OUTF;
;                 LAS float* ow0 = j == 0 ? ob + row : outb + 2 * GD_OUTF + l; const int omask = j == 0 ? -1 : 0;
; #pragma unroll 2
;                 for (int st = 0; st < TT; ++st) {
;                     const LAS float* sb = ib + st * GD_STRIDE;
;                     f32x2 kk[8], qq[8];
; #pragma unroll
;                     for (int e = 0; e < 4; ++e) { const f32x4 a = *(const LAS f32x4*)(sb + 20 * j + 4 * e), b = *(const LAS f32x4*)(sb + 160 + 20 * j + 4 * e);
;                         kk[2 * e] = (f32x2){a[0], a[1]}; kk[2 * e + 1] = (f32x2){a[2], a[3]}; qq[2 * e] = (f32x2){b[0], b[1]}; qq[2 * e + 1] = (f32x2){b[2], b[3]}; }
;                     const float v = sb[320 + row]; const f32x4 sc = *(const LAS f32x4*)(sb + 352); const float wdec = sc[0], cc = sc[1], kq = sc[2], beta = sc[3];
;                     f32x2 pa = sv[0] * kk[0], px = sv[0] * qq[0], pa2 = sv[1] * kk[1], px2 = sv[1] * qq[1];
; #pragma unroll
;                     for (int e = 2; e < 8; e += 2) { pa += sv[e] * kk[e]; px += sv[e] * qq[e]; pa2 += sv[e + 1] * kk[e + 1]; px2 += sv[e + 1] * qq[e + 1]; }
;                     pa += pa2; px += px2;
;                     const float sa = red8(pa[0] + pa[1]), x = red8(px[0] + px[1]);
;                     const float coef = beta * v - cc * sa; const float o = wdec * x + coef * kq;
;                     const f32x2 wd2 = (f32x2){wdec, wdec}, cf2 = (f32x2){coef, coef};
; #pragma unroll
;                     for (int e = 0; e < 8; ++e) sv[e] = sv[e] * wd2 + cf2 * kk[e];
;                     ow0[(st * 32) & omask] = o;
;                 }
;                 __syncthreads();
;             }
.Lgd_done:
	s_add_i32 s4, s4, 1
	s_xor_b64 s[0:1], s[0:1], -1
	s_cmpk_eq_i32 s4, 0x200
	s_waitcnt lgkmcnt(0)
	s_barrier
	s_cbranch_scc0 .LBB0_358
	s_branch .LBB0_172
